# baseline (speedup 1.0000x reference)
; #define LAS __attribute__((address_space(3)))
; #define LDS_WAIT() asm volatile("s_waitcnt lgkmcnt(0)" ::: "memory")
; __device__ __forceinline__ void dft2_mfma(const bf16_t* YB, bf16_t* Y, const bf16_t* A2, LAS unsigned char* tile, int gw, int NGW, int lane) {
;     ...
;         const int g = u & 3, ka = (u >> 2) & 127, b = u >> 9;
;         { u32x4 v[16];
; #pragma unroll
;           for (int it = 0; it < 16; ++it) { const int idx = it * 64 + lane, row = idx >> 4, chunk = idx & 15; v[it] = *(const u32x4*)(YB + (size_t)(b * SEQ + ka * 64 + row) * 512 + 128 * g + 8 * chunk); }
; #pragma unroll
;           for (int it = 0; it < 16; ++it) { const int idx = it * 64 + lane, row = idx >> 4, chunk = idx & 15; *(LAS u32x4*)(tile + row * 256 + (((chunk >> 2) ^ (row & 3)) * 64) + (chunk & 3) * 16) = v[it]; } }
;         LDS_WAIT();
;         f32x16 acc[2][2];
; #pragma unroll
;         for (int i = 0; i < 16; ++i) { acc[0][0][i] = 0.f; acc[0][1][i] = 0.f; acc[1][0][i] = 0.f; acc[1][1][i] = 0.f; }
; #pragma unroll
;         for (int kk = 0; kk < 8; ++kk) { const int part = kk >> 2, k4 = kk & 3; bf16x8 af[2], bfr[2];
; #pragma unroll
;             for (int mb = 0; mb < 2; ++mb) af[mb] = *(const bf16x8*)(A2 + (size_t)(32 * mb + r32) * 128 + 64 * part + 16 * k4 + 8 * hh);
.LBB0_528:
	s_bfe_u32 s6, s4, 0x70002
	s_and_b32 s5, s1, 0xffffe000
	s_lshl_b32 s7, s6, 6
	v_or_b32_e32 v4, s6, v188
	s_or_b32 s6, s7, s5
	v_or_b32_e32 v18, s6, v189
	v_or_b32_e32 v20, s6, v190
	v_or_b32_e32 v22, s6, v191
	v_or_b32_e32 v24, s6, v192
	v_or_b32_e32 v26, s6, v193
	v_or_b32_e32 v28, s6, v194
	v_or_b32_e32 v30, s6, v195
	v_or_b32_e32 v32, s6, v196
	v_or_b32_e32 v34, s6, v197
	v_or_b32_e32 v40, s6, v200
	v_or_b32_e32 v42, s6, v201
	v_or_b32_e32 v44, s6, v202
	v_or_b32_e32 v46, s6, v203
	v_or_b32_e32 v48, s6, v204
	v_or_b32_e32 v36, s6, v198
	v_or_b32_e32 v38, s6, v199
	v_ashrrev_i32_e32 v19, 31, v18
	v_ashrrev_i32_e32 v21, 31, v20
	v_ashrrev_i32_e32 v23, 31, v22
	v_ashrrev_i32_e32 v25, 31, v24
	v_ashrrev_i32_e32 v27, 31, v26
	v_ashrrev_i32_e32 v29, 31, v28
	v_ashrrev_i32_e32 v31, 31, v30
	v_ashrrev_i32_e32 v33, 31, v32
	v_ashrrev_i32_e32 v35, 31, v34
	v_ashrrev_i32_e32 v41, 31, v40
	v_ashrrev_i32_e32 v43, 31, v42
	v_ashrrev_i32_e32 v45, 31, v44
	v_ashrrev_i32_e32 v47, 31, v46
	v_ashrrev_i32_e32 v49, 31, v48
	v_ashrrev_i32_e32 v37, 31, v36
	v_ashrrev_i32_e32 v39, 31, v38
	v_lshlrev_b64 v[18:19], 10, v[18:19]
	v_lshlrev_b64 v[20:21], 10, v[20:21]
	v_lshlrev_b64 v[22:23], 10, v[22:23]
	v_lshlrev_b64 v[24:25], 10, v[24:25]
	v_lshlrev_b64 v[26:27], 10, v[26:27]
	v_lshlrev_b64 v[28:29], 10, v[28:29]
	v_lshlrev_b64 v[30:31], 10, v[30:31]
	v_lshlrev_b64 v[32:33], 10, v[32:33]
	v_lshlrev_b64 v[34:35], 10, v[34:35]
	v_lshlrev_b64 v[40:41], 10, v[40:41]
	v_lshlrev_b64 v[42:43], 10, v[42:43]
	v_lshlrev_b64 v[44:45], 10, v[44:45]
	v_lshlrev_b64 v[46:47], 10, v[46:47]
	v_lshlrev_b64 v[48:49], 10, v[48:49]
	v_lshlrev_b64 v[36:37], 10, v[36:37]
	v_lshlrev_b64 v[38:39], 10, v[38:39]
	v_lshl_add_u64 v[18:19], v[98:99], 0, v[18:19]
	v_lshl_add_u64 v[50:51], v[98:99], 0, v[20:21]
	v_lshl_add_u64 v[52:53], v[98:99], 0, v[22:23]
	v_lshl_add_u64 v[54:55], v[98:99], 0, v[24:25]
	v_lshl_add_u64 v[56:57], v[98:99], 0, v[26:27]
	v_lshl_add_u64 v[58:59], v[98:99], 0, v[28:29]
	v_lshl_add_u64 v[60:61], v[98:99], 0, v[30:31]
	v_lshl_add_u64 v[62:63], v[98:99], 0, v[32:33]
	v_lshl_add_u64 v[64:65], v[98:99], 0, v[34:35]
	v_lshl_add_u64 v[158:159], v[98:99], 0, v[40:41]
	v_lshl_add_u64 v[160:161], v[98:99], 0, v[42:43]
	v_lshl_add_u64 v[162:163], v[98:99], 0, v[44:45]
	v_lshl_add_u64 v[166:167], v[98:99], 0, v[46:47]
	v_lshl_add_u64 v[172:173], v[98:99], 0, v[48:49]
	v_lshl_add_u64 v[66:67], v[98:99], 0, v[36:37]
	v_lshl_add_u64 v[102:103], v[98:99], 0, v[38:39]
	global_load_dwordx4 v[18:21], v[18:19], off
	s_nop 0
	global_load_dwordx4 v[22:25], v[50:51], off
	global_load_dwordx4 v[26:29], v[52:53], off
	global_load_dwordx4 v[30:33], v[54:55], off
	global_load_dwordx4 v[34:37], v[56:57], off
	global_load_dwordx4 v[38:41], v[58:59], off
	global_load_dwordx4 v[42:45], v[60:61], off
	global_load_dwordx4 v[46:49], v[62:63], off
	global_load_dwordx4 v[50:53], v[64:65], off
	s_nop 0
	global_load_dwordx4 v[54:57], v[66:67], off
	global_load_dwordx4 v[58:61], v[102:103], off
	global_load_dwordx4 v[62:65], v[158:159], off
	s_nop 0
	global_load_dwordx4 v[158:161], v[160:161], off
	s_nop 0
	global_load_dwordx4 v[162:165], v[162:163], off
	s_nop 0
	global_load_dwordx4 v[166:169], v[166:167], off
	s_nop 0
	global_load_dwordx4 v[172:175], v[172:173], off
	global_load_dwordx4 v[240:243], v[0:1], off
	global_load_dwordx4 v[244:247], v[68:69], off
	global_load_dwordx4 v[250:253], v[70:71], off
	v_add_u32_e32 v170, v3, v205
	v_or_b32_e32 v16, s5, v4
	v_ashrrev_i32_e32 v17, 31, v16
	v_or_b32_e32 v4, 0x80, v16
	v_or_b32_e32 v6, 0x100, v16
	v_or_b32_e32 v8, 0x180, v16
	v_or_b32_e32 v10, 0x400, v16
	v_or_b32_e32 v12, 0x480, v16
	v_or_b32_e32 v14, 0x500, v16
	v_or_b32_e32 v156, 0x580, v16
	v_or_b32_e32 v142, 0x800, v16
	v_or_b32_e32 v144, 0x880, v16
	v_or_b32_e32 v146, 0x900, v16
	v_or_b32_e32 v148, 0x980, v16
	v_or_b32_e32 v150, 0xc00, v16
	v_or_b32_e32 v152, 0xc80, v16
	v_or_b32_e32 v154, 0xd00, v16
	s_waitcnt vmcnt(0) lgkmcnt(0)
	ds_write_b128 v206, v[18:21]
	ds_write_b128 v207, v[22:25]
	ds_write_b128 v213, v[26:29]
	ds_write_b128 v214, v[30:33]
	ds_write_b128 v215, v[34:37]
	ds_write_b128 v216, v[38:41]
	ds_write_b128 v217, v[42:45]
	ds_write_b128 v218, v[46:49]
	ds_write_b128 v219, v[50:53]
	ds_write_b128 v220, v[54:57]
	ds_write_b128 v221, v[58:61]
	ds_write_b128 v222, v[62:65]
	ds_write_b128 v223, v[158:161]
	ds_write_b128 v224, v[162:165]
	ds_write_b128 v225, v[166:169]
	ds_write_b128 v226, v[172:175]
	s_waitcnt lgkmcnt(0)
	ds_read_b64_tr_b16 v[36:37], v170
	ds_read_b64_tr_b16 v[38:39], v170 offset:1024
	ds_read_b64_tr_b16 v[172:173], v227
	ds_read_b64_tr_b16 v[174:175], v227 offset:1024
	v_or_b32_e32 v140, 0xd80, v16
	v_or_b32_e32 v122, 0x1000, v16
	v_or_b32_e32 v124, 0x1080, v16
	v_or_b32_e32 v126, 0x1100, v16
	v_or_b32_e32 v128, 0x1180, v16
	v_or_b32_e32 v130, 0x1400, v16
	v_or_b32_e32 v136, 0x1480, v16
	v_or_b32_e32 v138, 0x1500, v16
	v_or_b32_e32 v120, 0x1580, v16
	v_or_b32_e32 v106, 0x1800, v16
	v_or_b32_e32 v108, 0x1880, v16
	v_or_b32_e32 v110, 0x1900, v16
	v_or_b32_e32 v112, 0x1980, v16
	v_or_b32_e32 v114, 0x1c00, v16
	v_or_b32_e32 v116, 0x1c80, v16
	v_or_b32_e32 v118, 0x1d00, v16
	v_or_b32_e32 v104, 0x1d80, v16
	v_lshlrev_b64 v[16:17], 11, v[16:17]
	v_ashrrev_i32_e32 v5, 31, v4
	v_ashrrev_i32_e32 v7, 31, v6
	v_ashrrev_i32_e32 v9, 31, v8
	v_ashrrev_i32_e32 v11, 31, v10
	v_ashrrev_i32_e32 v13, 31, v12
	v_ashrrev_i32_e32 v15, 31, v14
	s_waitcnt vmcnt(0) lgkmcnt(0)
; __device__ __forceinline__ void dft2_mfma(const bf16_t* YB, bf16_t* Y, const bf16_t* A2, LAS unsigned char* tile, int gw, int NGW, int lane) {
;     ...
;         for (int kk = 0; kk < 8; ++kk) { const int part = kk >> 2, k4 = kk & 3; bf16x8 af[2], bfr[2];
; #pragma unroll
;             for (int mb = 0; mb < 2; ++mb) af[mb] = *(const bf16x8*)(A2 + (size_t)(32 * mb + r32) * 128 + 64 * part + 16 * k4 + 8 * hh);
; #pragma unroll
;             for (int nb = 0; nb < 2; ++nb) bfr[nb] = tr2(tile + rbase + k4 * 4096 + (((2 * part + nb) ^ q) * 64), 1024);
; #pragma unroll
;             for (int mb = 0; mb < 2; ++mb)
; #pragma unroll
;                 for (int nb = 0; nb < 2; ++nb) acc[mb][nb] = __builtin_amdgcn_mfma_f32_32x32x16_bf16(af[mb], bfr[nb], acc[mb][nb], 0, 0, 0); }
	v_mfma_f32_32x32x16_bf16 v[52:67], v[240:243], v[36:39], 0
	v_lshl_add_u64 v[102:103], v[100:101], 0, v[16:17]
	v_lshlrev_b64 v[158:159], 11, v[4:5]
	v_lshlrev_b64 v[160:161], 11, v[6:7]
	v_lshlrev_b64 v[162:163], 11, v[8:9]
	v_lshlrev_b64 v[164:165], 11, v[10:11]
	v_lshlrev_b64 v[166:167], 11, v[12:13]
	v_lshlrev_b64 v[168:169], 11, v[14:15]
	v_mfma_f32_32x32x16_bf16 v[20:35], v[240:243], v[172:175], 0
	v_ashrrev_i32_e32 v157, 31, v156
	v_ashrrev_i32_e32 v143, 31, v142
	v_ashrrev_i32_e32 v145, 31, v144
	v_ashrrev_i32_e32 v147, 31, v146
	v_ashrrev_i32_e32 v149, 31, v148
	v_ashrrev_i32_e32 v151, 31, v150
	v_ashrrev_i32_e32 v153, 31, v152
	v_mfma_f32_32x32x16_bf16 v[4:19], v[244:247], v[172:175], 0
	ds_read_b64_tr_b16 v[180:181], v170 offset:4096
	ds_read_b64_tr_b16 v[182:183], v170 offset:5120
	ds_read_b64_tr_b16 v[230:231], v227 offset:4096
	ds_read_b64_tr_b16 v[232:233], v227 offset:5120
	v_ashrrev_i32_e32 v155, 31, v154
	v_ashrrev_i32_e32 v141, 31, v140
	v_ashrrev_i32_e32 v123, 31, v122
	v_ashrrev_i32_e32 v125, 31, v124
	s_waitcnt vmcnt(0) lgkmcnt(0)
	v_mfma_f32_32x32x16_bf16 v[52:67], v[250:253], v[180:183], v[52:67]
	v_ashrrev_i32_e32 v127, 31, v126
	v_ashrrev_i32_e32 v129, 31, v128
	v_ashrrev_i32_e32 v131, 31, v130
	v_ashrrev_i32_e32 v137, 31, v136
	v_ashrrev_i32_e32 v139, 31, v138
	v_ashrrev_i32_e32 v121, 31, v120
	v_ashrrev_i32_e32 v107, 31, v106
	v_mfma_f32_32x32x16_bf16 v[20:35], v[250:253], v[230:233], v[20:35]
	global_load_dwordx4 v[172:175], v[72:73], off
	v_ashrrev_i32_e32 v109, 31, v108
	v_ashrrev_i32_e32 v111, 31, v110
	v_ashrrev_i32_e32 v113, 31, v112
	v_lshlrev_b64 v[184:185], 11, v[106:107]
	v_ashrrev_i32_e32 v115, 31, v114
	v_ashrrev_i32_e32 v105, 31, v104
	v_mfma_f32_32x32x16_bf16 v[36:51], v[244:247], v[36:39], 0
	v_lshlrev_b64 v[178:179], 11, v[156:157]
	v_lshlrev_b64 v[176:177], 11, v[104:105]
	v_lshl_add_u64 v[104:105], v[100:101], 0, v[158:159]
	v_ashrrev_i32_e32 v117, 31, v116
	v_ashrrev_i32_e32 v119, 31, v118
	s_add_i32 s4, s4, s12
	s_add_i32 s1, s1, s3
	s_waitcnt vmcnt(0) lgkmcnt(0)
	v_mfma_f32_32x32x16_bf16 v[36:51], v[172:175], v[180:183], v[36:51]
	v_lshlrev_b64 v[182:183], 11, v[142:143]
	v_lshlrev_b64 v[142:143], 11, v[144:145]
	v_lshlrev_b64 v[144:145], 11, v[146:147]
	v_lshlrev_b64 v[146:147], 11, v[148:149]
	v_lshlrev_b64 v[148:149], 11, v[150:151]
	v_lshlrev_b64 v[150:151], 11, v[152:153]
	v_lshlrev_b64 v[152:153], 11, v[154:155]
	global_load_dwordx4 v[154:157], v[74:75], off
	v_mfma_f32_32x32x16_bf16 v[4:19], v[172:175], v[230:233], v[4:19]
	ds_read_b64_tr_b16 v[230:231], v170 offset:8192
	ds_read_b64_tr_b16 v[232:233], v170 offset:9216
	ds_read_b64_tr_b16 v[234:235], v227 offset:8192
	ds_read_b64_tr_b16 v[236:237], v227 offset:9216
	v_lshlrev_b64 v[174:175], 11, v[140:141]
	v_lshlrev_b64 v[172:173], 11, v[122:123]
	v_lshlrev_b64 v[122:123], 11, v[124:125]
	v_lshlrev_b64 v[124:125], 11, v[126:127]
	v_lshlrev_b64 v[126:127], 11, v[128:129]
	s_waitcnt vmcnt(0) lgkmcnt(0)
	v_mfma_f32_32x32x16_bf16 v[52:67], v[154:157], v[230:233], v[52:67]
	v_lshlrev_b64 v[128:129], 11, v[130:131]
	v_lshlrev_b64 v[130:131], 11, v[136:137]
	v_lshlrev_b64 v[136:137], 11, v[138:139]
	global_load_dwordx4 v[138:141], v[78:79], off
	v_lshlrev_b64 v[180:181], 11, v[120:121]
	v_lshlrev_b64 v[120:121], 11, v[108:109]
	v_lshl_add_u64 v[142:143], v[100:101], 0, v[142:143]
	v_mfma_f32_32x32x16_bf16 v[20:35], v[154:157], v[234:237], v[20:35]
	global_load_dwordx4 v[154:157], v[76:77], off
	v_lshl_add_u64 v[144:145], v[100:101], 0, v[144:145]
	v_lshl_add_u64 v[146:147], v[100:101], 0, v[146:147]
	v_lshl_add_u64 v[148:149], v[100:101], 0, v[148:149]
	v_lshl_add_u64 v[150:151], v[100:101], 0, v[150:151]
	v_lshl_add_u64 v[152:153], v[100:101], 0, v[152:153]
	v_lshl_add_u64 v[122:123], v[100:101], 0, v[122:123]
	s_waitcnt vmcnt(0) lgkmcnt(0)
	v_mfma_f32_32x32x16_bf16 v[36:51], v[154:157], v[230:233], v[36:51]
	v_lshl_add_u64 v[124:125], v[100:101], 0, v[124:125]
	v_lshl_add_u64 v[126:127], v[100:101], 0, v[126:127]
	v_lshl_add_u64 v[128:129], v[100:101], 0, v[128:129]
	v_lshl_add_u64 v[130:131], v[100:101], 0, v[130:131]
	v_lshl_add_u64 v[136:137], v[100:101], 0, v[136:137]
	v_lshl_add_u64 v[120:121], v[100:101], 0, v[120:121]
	s_cmpk_lt_i32 s4, 0x800
	v_mfma_f32_32x32x16_bf16 v[4:19], v[154:157], v[234:237], v[4:19]
	ds_read_b64_tr_b16 v[154:155], v170 offset:12288
	ds_read_b64_tr_b16 v[156:157], v170 offset:13312
	ds_read_b64_tr_b16 v[230:231], v227 offset:12288
	ds_read_b64_tr_b16 v[232:233], v227 offset:13312
	global_load_dwordx4 v[234:237], v[80:81], off
	global_load_dwordx4 v[106:109], v[82:83], off
	v_lshlrev_b64 v[170:171], 11, v[118:119]
	v_lshl_add_u64 v[118:119], v[100:101], 0, v[182:183]
	v_lshl_add_u64 v[170:171], v[100:101], 0, v[170:171]
	s_waitcnt lgkmcnt(0)
	v_mfma_f32_32x32x16_bf16 v[52:67], v[138:141], v[154:157], v[52:67]
	v_mfma_f32_32x32x16_bf16 v[20:35], v[138:141], v[230:233], v[20:35]
	v_lshlrev_b64 v[138:139], 11, v[110:111]
	v_lshlrev_b64 v[140:141], 11, v[112:113]
	ds_read_b64_tr_b16 v[110:111], v228
	ds_read_b64_tr_b16 v[112:113], v228 offset:1024
	v_lshl_add_u64 v[138:139], v[100:101], 0, v[138:139]
	v_lshl_add_u64 v[140:141], v[100:101], 0, v[140:141]
	s_waitcnt vmcnt(0)
	v_mfma_f32_32x32x16_bf16 v[36:51], v[234:237], v[154:157], v[36:51]
	v_lshlrev_b64 v[154:155], 11, v[114:115]
	v_lshl_add_u64 v[114:115], v[100:101], 0, v[168:169]
	v_lshlrev_b64 v[156:157], 11, v[116:117]
	v_lshl_add_u64 v[116:117], v[100:101], 0, v[178:179]
	v_lshl_add_u64 v[154:155], v[100:101], 0, v[154:155]
	v_lshl_add_u64 v[156:157], v[100:101], 0, v[156:157]
	v_mfma_f32_32x32x16_bf16 v[4:19], v[234:237], v[230:233], v[4:19]
	ds_read_b64_tr_b16 v[230:231], v229
	ds_read_b64_tr_b16 v[232:233], v229 offset:1024
	global_load_dwordx4 v[234:237], v[84:85], off
	s_waitcnt lgkmcnt(0)
; __device__ __forceinline__ bf16_t bf1(float v) { return (bf16_t)pk2(v, 0.f); }
; __device__ __forceinline__ void dft2_mfma(const bf16_t* YB, bf16_t* Y, const bf16_t* A2, LAS unsigned char* tile, int gw, int NGW, int lane) {
;     ...
;         for (int kk = 0; kk < 8; ++kk) { const int part = kk >> 2, k4 = kk & 3; bf16x8 af[2], bfr[2];
; #pragma unroll
;             for (int mb = 0; mb < 2; ++mb) af[mb] = *(const bf16x8*)(A2 + (size_t)(32 * mb + r32) * 128 + 64 * part + 16 * k4 + 8 * hh);
; #pragma unroll
;             for (int nb = 0; nb < 2; ++nb) bfr[nb] = tr2(tile + rbase + k4 * 4096 + (((2 * part + nb) ^ q) * 64), 1024);
; #pragma unroll
;             for (int mb = 0; mb < 2; ++mb)
; #pragma unroll
;                 for (int nb = 0; nb < 2; ++nb) acc[mb][nb] = __builtin_amdgcn_mfma_f32_32x32x16_bf16(af[mb], bfr[nb], acc[mb][nb], 0, 0, 0); }
; #pragma unroll
;         for (int mb = 0; mb < 2; ++mb)
; #pragma unroll
;             for (int nb = 0; nb < 2; ++nb)
; #pragma unroll
;                 for (int i = 0; i < 16; ++i) { const int kb = 32 * mb + 8 * (i >> 2) + 4 * hh + (i & 3), k = ka + 128 * kb;
;                     Y[(size_t)(b * SEQ + k) * DM + 256 + 64 * g + 32 * nb + r32] = bf1(acc[mb][nb][i] * scale); }
	v_mfma_f32_32x32x16_bf16 v[52:67], v[106:109], v[110:113], v[52:67]
	v_mfma_f32_32x32x16_bf16 v[20:35], v[106:109], v[230:233], v[20:35]
	v_lshl_add_u64 v[106:107], v[100:101], 0, v[160:161]
	v_lshl_add_u64 v[108:109], v[100:101], 0, v[162:163]
	global_load_dwordx4 v[158:161], v[86:87], off
	s_waitcnt vmcnt(0)
	v_mfma_f32_32x32x16_bf16 v[36:51], v[234:237], v[110:113], v[36:51]
	v_lshl_add_u64 v[110:111], v[100:101], 0, v[164:165]
	v_lshl_add_u64 v[112:113], v[100:101], 0, v[166:167]
	ds_read_b64_tr_b16 v[162:163], v228 offset:4096
	ds_read_b64_tr_b16 v[164:165], v228 offset:5120
	ds_read_b64_tr_b16 v[166:167], v229 offset:4096
	ds_read_b64_tr_b16 v[168:169], v229 offset:5120
	v_mfma_f32_32x32x16_bf16 v[4:19], v[234:237], v[230:233], v[4:19]
	global_load_dwordx4 v[230:233], v[88:89], off
	s_waitcnt lgkmcnt(0)
	v_mfma_f32_32x32x16_bf16 v[52:67], v[158:161], v[162:165], v[52:67]
	v_mfma_f32_32x32x16_bf16 v[20:35], v[158:161], v[166:169], v[20:35]
	v_lshl_add_u64 v[158:159], v[100:101], 0, v[174:175]
	v_lshl_add_u64 v[160:161], v[100:101], 0, v[172:173]
	s_waitcnt vmcnt(0)
	v_mfma_f32_32x32x16_bf16 v[36:51], v[230:233], v[162:165], v[36:51]
	global_load_dwordx4 v[162:165], v[90:91], off
	v_mfma_f32_32x32x16_bf16 v[4:19], v[230:233], v[166:169], v[4:19]
	ds_read_b64_tr_b16 v[166:167], v228 offset:8192
	ds_read_b64_tr_b16 v[168:169], v228 offset:9216
	ds_read_b64_tr_b16 v[172:173], v229 offset:8192
	ds_read_b64_tr_b16 v[174:175], v229 offset:9216
	global_load_dwordx4 v[230:233], v[92:93], off
	s_waitcnt vmcnt(0) lgkmcnt(0)
	v_mfma_f32_32x32x16_bf16 v[52:67], v[162:165], v[166:169], v[52:67]
	v_mfma_f32_32x32x16_bf16 v[36:51], v[230:233], v[166:169], v[36:51]
	global_load_dwordx4 v[166:169], v[94:95], off
	v_mfma_f32_32x32x16_bf16 v[20:35], v[162:165], v[172:175], v[20:35]
	v_lshl_add_u64 v[162:163], v[100:101], 0, v[180:181]
	v_lshl_add_u64 v[164:165], v[100:101], 0, v[184:185]
	v_mfma_f32_32x32x16_bf16 v[4:19], v[230:233], v[172:175], v[4:19]
	ds_read_b64_tr_b16 v[172:173], v228 offset:12288
	ds_read_b64_tr_b16 v[174:175], v228 offset:13312
	ds_read_b64_tr_b16 v[178:179], v229 offset:12288
	ds_read_b64_tr_b16 v[180:181], v229 offset:13312
	s_waitcnt vmcnt(0) lgkmcnt(0)
	v_mfma_f32_32x32x16_bf16 v[52:67], v[166:169], v[172:175], v[52:67]
	s_nop 11
	v_mul_f32_e32 v52, 0x3ab504f3, v52
	v_mfma_f32_32x32x16_bf16 v[20:35], v[166:169], v[178:181], v[20:35]
	global_load_dwordx4 v[166:169], v[96:97], off
	v_mul_f32_e32 v53, 0x3ab504f3, v53
	v_mul_f32_e32 v54, 0x3ab504f3, v54
	v_mul_f32_e32 v55, 0x3ab504f3, v55
	v_mul_f32_e32 v56, 0x3ab504f3, v56
	v_mul_f32_e32 v57, 0x3ab504f3, v57
	v_mul_f32_e32 v58, 0x3ab504f3, v58
	s_waitcnt vmcnt(0) lgkmcnt(0)
	v_mfma_f32_32x32x16_bf16 v[36:51], v[166:169], v[172:175], v[36:51]
	v_mul_f32_e32 v59, 0x3ab504f3, v59
	v_mul_f32_e32 v60, 0x3ab504f3, v60
	v_mul_f32_e32 v61, 0x3ab504f3, v61
	v_mul_f32_e32 v62, 0x3ab504f3, v62
	v_mul_f32_e32 v63, 0x3ab504f3, v63
	v_mul_f32_e32 v64, 0x3ab504f3, v64
	v_mul_f32_e32 v65, 0x3ab504f3, v65
	v_mfma_f32_32x32x16_bf16 v[4:19], v[166:169], v[178:181], v[4:19]
	v_mul_f32_e32 v66, 0x3ab504f3, v66
	v_mul_f32_e32 v67, 0x3ab504f3, v67
	v_mul_f32_e32 v20, 0x3ab504f3, v20
	v_mul_f32_e32 v21, 0x3ab504f3, v21
	v_mul_f32_e32 v22, 0x3ab504f3, v22
	v_mul_f32_e32 v23, 0x3ab504f3, v23
	v_mul_f32_e32 v24, 0x3ab504f3, v24
	v_mul_f32_e32 v25, 0x3ab504f3, v25
	v_mul_f32_e32 v26, 0x3ab504f3, v26
	v_mul_f32_e32 v27, 0x3ab504f3, v27
	v_mul_f32_e32 v28, 0x3ab504f3, v28
	v_mul_f32_e32 v29, 0x3ab504f3, v29
	v_mul_f32_e32 v30, 0x3ab504f3, v30
	v_mul_f32_e32 v31, 0x3ab504f3, v31
	v_mul_f32_e32 v32, 0x3ab504f3, v32
	v_mul_f32_e32 v33, 0x3ab504f3, v33
	v_mul_f32_e32 v34, 0x3ab504f3, v34
	v_mul_f32_e32 v35, 0x3ab504f3, v35
	v_mul_f32_e32 v36, 0x3ab504f3, v36
	v_mul_f32_e32 v37, 0x3ab504f3, v37
	v_mul_f32_e32 v38, 0x3ab504f3, v38
	v_mul_f32_e32 v39, 0x3ab504f3, v39
	v_mul_f32_e32 v40, 0x3ab504f3, v40
	v_mul_f32_e32 v41, 0x3ab504f3, v41
	v_mul_f32_e32 v42, 0x3ab504f3, v42
	v_mul_f32_e32 v43, 0x3ab504f3, v43
	v_mul_f32_e32 v44, 0x3ab504f3, v44
	v_mul_f32_e32 v45, 0x3ab504f3, v45
	v_mul_f32_e32 v46, 0x3ab504f3, v46
	v_mul_f32_e32 v47, 0x3ab504f3, v47
	v_mul_f32_e32 v48, 0x3ab504f3, v48
	v_mul_f32_e32 v49, 0x3ab504f3, v49
	v_mul_f32_e32 v50, 0x3ab504f3, v50
	v_mul_f32_e32 v51, 0x3ab504f3, v51
	v_mul_f32_e32 v4, 0x3ab504f3, v4
	v_mul_f32_e32 v5, 0x3ab504f3, v5
	v_mul_f32_e32 v6, 0x3ab504f3, v6
	v_mul_f32_e32 v7, 0x3ab504f3, v7
	v_mul_f32_e32 v8, 0x3ab504f3, v8
	v_mul_f32_e32 v9, 0x3ab504f3, v9
	v_mul_f32_e32 v10, 0x3ab504f3, v10
	v_mul_f32_e32 v11, 0x3ab504f3, v11
	v_mul_f32_e32 v12, 0x3ab504f3, v12
	v_mul_f32_e32 v13, 0x3ab504f3, v13
	v_mul_f32_e32 v14, 0x3ab504f3, v14
	v_mul_f32_e32 v15, 0x3ab504f3, v15
	v_mul_f32_e32 v16, 0x3ab504f3, v16
	v_mul_f32_e32 v17, 0x3ab504f3, v17
	v_mul_f32_e32 v18, 0x3ab504f3, v18
	v_mul_f32_e32 v19, 0x3ab504f3, v19
	v_cvt_pk_bf16_f32 v52, v52, s0
	v_lshl_add_u64 v[172:173], v[100:101], 0, v[176:177]
	v_cvt_pk_bf16_f32 v53, v53, s0
	v_cvt_pk_bf16_f32 v54, v54, s0
	v_cvt_pk_bf16_f32 v55, v55, s0
	v_cvt_pk_bf16_f32 v56, v56, s0
	v_cvt_pk_bf16_f32 v57, v57, s0
	v_cvt_pk_bf16_f32 v58, v58, s0
	v_cvt_pk_bf16_f32 v59, v59, s0
; __device__ __forceinline__ bf16_t bf1(float v) { return (bf16_t)pk2(v, 0.f); }
; #define LDS_WAIT() asm volatile("s_waitcnt lgkmcnt(0)" ::: "memory")
; __device__ __forceinline__ void dft2_mfma(const bf16_t* YB, bf16_t* Y, const bf16_t* A2, LAS unsigned char* tile, int gw, int NGW, int lane) {
;     ...
; #pragma unroll
;         for (int mb = 0; mb < 2; ++mb)
; #pragma unroll
;             for (int nb = 0; nb < 2; ++nb)
; #pragma unroll
;                 for (int i = 0; i < 16; ++i) { const int kb = 32 * mb + 8 * (i >> 2) + 4 * hh + (i & 3), k = ka + 128 * kb;
;                     Y[(size_t)(b * SEQ + k) * DM + 256 + 64 * g + 32 * nb + r32] = bf1(acc[mb][nb][i] * scale); }
;         LDS_WAIT();
	v_cvt_pk_bf16_f32 v60, v60, s0
	v_cvt_pk_bf16_f32 v61, v61, s0
	v_cvt_pk_bf16_f32 v62, v62, s0
	v_cvt_pk_bf16_f32 v63, v63, s0
	v_cvt_pk_bf16_f32 v64, v64, s0
	v_cvt_pk_bf16_f32 v65, v65, s0
	v_cvt_pk_bf16_f32 v66, v66, s0
	v_cvt_pk_bf16_f32 v67, v67, s0
	v_cvt_pk_bf16_f32 v20, v20, s0
	v_cvt_pk_bf16_f32 v21, v21, s0
	v_cvt_pk_bf16_f32 v22, v22, s0
	v_cvt_pk_bf16_f32 v23, v23, s0
	v_cvt_pk_bf16_f32 v24, v24, s0
	v_cvt_pk_bf16_f32 v25, v25, s0
	v_cvt_pk_bf16_f32 v26, v26, s0
	v_cvt_pk_bf16_f32 v27, v27, s0
	v_cvt_pk_bf16_f32 v28, v28, s0
	v_cvt_pk_bf16_f32 v29, v29, s0
	v_cvt_pk_bf16_f32 v30, v30, s0
	v_cvt_pk_bf16_f32 v31, v31, s0
	v_cvt_pk_bf16_f32 v32, v32, s0
	v_cvt_pk_bf16_f32 v33, v33, s0
	v_cvt_pk_bf16_f32 v34, v34, s0
	v_cvt_pk_bf16_f32 v35, v35, s0
	v_cvt_pk_bf16_f32 v36, v36, s0
	v_cvt_pk_bf16_f32 v37, v37, s0
	v_cvt_pk_bf16_f32 v38, v38, s0
	v_cvt_pk_bf16_f32 v39, v39, s0
	v_cvt_pk_bf16_f32 v40, v40, s0
	v_cvt_pk_bf16_f32 v41, v41, s0
	v_cvt_pk_bf16_f32 v42, v42, s0
	v_cvt_pk_bf16_f32 v43, v43, s0
	v_cvt_pk_bf16_f32 v44, v44, s0
	v_cvt_pk_bf16_f32 v45, v45, s0
	v_cvt_pk_bf16_f32 v46, v46, s0
	v_cvt_pk_bf16_f32 v47, v47, s0
	v_cvt_pk_bf16_f32 v48, v48, s0
	v_cvt_pk_bf16_f32 v49, v49, s0
	v_cvt_pk_bf16_f32 v50, v50, s0
	v_cvt_pk_bf16_f32 v51, v51, s0
	v_cvt_pk_bf16_f32 v4, v4, s0
	v_cvt_pk_bf16_f32 v5, v5, s0
	v_cvt_pk_bf16_f32 v6, v6, s0
	v_cvt_pk_bf16_f32 v7, v7, s0
	v_cvt_pk_bf16_f32 v8, v8, s0
	v_cvt_pk_bf16_f32 v9, v9, s0
	v_cvt_pk_bf16_f32 v10, v10, s0
	v_cvt_pk_bf16_f32 v11, v11, s0
	v_cvt_pk_bf16_f32 v12, v12, s0
	v_cvt_pk_bf16_f32 v13, v13, s0
	v_cvt_pk_bf16_f32 v14, v14, s0
	v_cvt_pk_bf16_f32 v15, v15, s0
	v_cvt_pk_bf16_f32 v16, v16, s0
	v_cvt_pk_bf16_f32 v17, v17, s0
	v_cvt_pk_bf16_f32 v18, v18, s0
	v_cvt_pk_bf16_f32 v19, v19, s0
	global_store_short v[102:103], v52, off offset:512
	global_store_short v[104:105], v53, off offset:512
	global_store_short v[106:107], v54, off offset:512
	global_store_short v[108:109], v55, off offset:512
	global_store_short v[110:111], v56, off offset:512
	global_store_short v[112:113], v57, off offset:512
	global_store_short v[114:115], v58, off offset:512
	global_store_short v[116:117], v59, off offset:512
	global_store_short v[118:119], v60, off offset:512
	global_store_short v[142:143], v61, off offset:512
	global_store_short v[144:145], v62, off offset:512
	global_store_short v[146:147], v63, off offset:512
	global_store_short v[148:149], v64, off offset:512
	global_store_short v[150:151], v65, off offset:512
	global_store_short v[152:153], v66, off offset:512
	global_store_short v[158:159], v67, off offset:512
	global_store_short v[102:103], v20, off offset:576
	global_store_short v[104:105], v21, off offset:576
	global_store_short v[106:107], v22, off offset:576
	global_store_short v[108:109], v23, off offset:576
	global_store_short v[110:111], v24, off offset:576
	global_store_short v[112:113], v25, off offset:576
	global_store_short v[114:115], v26, off offset:576
	global_store_short v[116:117], v27, off offset:576
	global_store_short v[118:119], v28, off offset:576
	global_store_short v[142:143], v29, off offset:576
	global_store_short v[144:145], v30, off offset:576
	global_store_short v[146:147], v31, off offset:576
	global_store_short v[148:149], v32, off offset:576
	global_store_short v[150:151], v33, off offset:576
	global_store_short v[152:153], v34, off offset:576
	global_store_short v[158:159], v35, off offset:576
	global_store_short v[160:161], v36, off offset:512
	global_store_short v[122:123], v37, off offset:512
	global_store_short v[124:125], v38, off offset:512
	global_store_short v[126:127], v39, off offset:512
	global_store_short v[128:129], v40, off offset:512
	global_store_short v[130:131], v41, off offset:512
	global_store_short v[136:137], v42, off offset:512
	global_store_short v[162:163], v43, off offset:512
	global_store_short v[164:165], v44, off offset:512
	global_store_short v[120:121], v45, off offset:512
	global_store_short v[138:139], v46, off offset:512
	global_store_short v[140:141], v47, off offset:512
	global_store_short v[154:155], v48, off offset:512
	global_store_short v[156:157], v49, off offset:512
	global_store_short v[170:171], v50, off offset:512
	global_store_short v[172:173], v51, off offset:512
	global_store_short v[160:161], v4, off offset:576
	global_store_short v[122:123], v5, off offset:576
	global_store_short v[124:125], v6, off offset:576
	global_store_short v[126:127], v7, off offset:576
	global_store_short v[128:129], v8, off offset:576
	global_store_short v[130:131], v9, off offset:576
	global_store_short v[136:137], v10, off offset:576
	global_store_short v[162:163], v11, off offset:576
	global_store_short v[164:165], v12, off offset:576
	global_store_short v[120:121], v13, off offset:576
	global_store_short v[138:139], v14, off offset:576
	global_store_short v[140:141], v15, off offset:576
	global_store_short v[154:155], v16, off offset:576
	global_store_short v[156:157], v17, off offset:576
	global_store_short v[170:171], v18, off offset:576
	global_store_short v[172:173], v19, off offset:576
	s_waitcnt lgkmcnt(0)
	s_cbranch_scc1 .LBB0_528
